# v75 + non-temporal hint on P7's read-once streaming loads (importance rows, q, combine pieces); K/V block loads unchanged
# baseline (speedup 1.0000x reference)
.LBB0_782:
	s_lshl_b32 s1, s96, 13
	s_bfe_u32 s0, s96, 0x20001
	s_and_b32 s1, s1, 0x2000
	s_and_b32 s2, s96, -8
	s_lshl_b32 s2, s2, 2
	s_lshl_b32 s4, s0, 24
	s_lshl_b32 s41, s0, 21
	s_add_i32 s0, s1, s2
	v_readlane_b32 s1, v235, 17
	s_lshl_b32 s1, s1, 2
	s_lshl_b32 s3, s96, 12
	s_add_i32 s0, s0, s1
	s_bfe_u32 s9, s96, 0x10001
	s_and_b32 s3, s3, 0x4000
	s_ashr_i32 s1, s0, 31
	s_add_u32 s2, s0, s3
	s_addc_u32 s8, s1, 0
	v_readlane_b32 s5, v234, 7
	s_add_u32 s4, s5, s4
	v_readlane_b32 s5, v234, 8
	v_mbcnt_lo_u32_b32 v10, -1, 0
	v_mbcnt_hi_u32_b32 v10, -1, v10
	s_addc_u32 s5, s5, 0
	s_lshl_b64 s[6:7], s[0:1], 10
	v_lshlrev_b32_e32 v104, 2, v10
	v_lshlrev_b32_e32 v180, 4, v10
	v_bfe_u32 v232, v10, 2, 2
	v_mul_u32_u24_e32 v233, 0x4e00, v232
	s_add_u32 s6, s4, s6
	v_ashrrev_i32_e32 v105, 31, v104
	s_addc_u32 s7, s5, s7
	v_lshlrev_b64 v[2:3], 2, v[104:105]
	v_lshl_add_u64 v[0:1], s[6:7], 0, v[2:3]
	s_mulk_i32 s8, 0x4e00
	s_mul_hi_u32 s1, s2, 0x4e00
	v_lshlrev_b32_e32 v0, 8, v10
	s_add_i32 s1, s1, s8
	s_mulk_i32 s2, 0x4e00
	v_and_b32_e32 v0, 0x300, v0
	v_lshlrev_b32_e32 v1, 1, v10
	s_add_u32 s6, s94, s2
	v_lshl_or_b32 v4, s9, 10, v0
	v_add_u32_e32 v4, v4, v233
	v_mov_b32_e32 v0, 0
	v_and_b32_e32 v8, 0xffffffe0, v1
	s_addc_u32 s7, s95, s1
	v_mov_b32_e32 v5, v0
	v_ashrrev_i32_e32 v9, 31, v8
	v_lshl_add_u64 v[6:7], s[6:7], 0, v[4:5]
	v_lshlrev_b64 v[8:9], 1, v[8:9]
	v_lshl_add_u64 v[6:7], v[6:7], 0, v[8:9]
	global_load_dwordx4 v[36:39], v[6:7], off nt
	global_load_dwordx4 v[32:35], v[6:7], off offset:16 nt
	global_load_dwordx4 v[28:31], v[6:7], off offset:32 nt
	global_load_dwordx4 v[24:27], v[6:7], off offset:48 nt
	v_lshl_add_u64 v[106:107], s[4:5], 0, v[2:3]
	v_lshl_add_u64 v[2:3], s[94:95], 0, v[4:5]
	v_lshl_add_u64 v[108:109], v[2:3], 0, v[8:9]
	v_lshlrev_b32_e32 v2, 4, v10
	v_readlane_b32 s10, v235, 48
	s_lshl_b32 s2, s9, 2
	v_ashrrev_i32_e32 v3, 31, v2
	v_readlane_b32 s11, v235, 49
	v_and_or_b32 v4, v10, 3, s2
	v_and_b32_e32 v1, 12, v10
	v_lshl_add_u64 v[112:113], s[10:11], 0, v[2:3]
	v_readlane_b32 s10, v235, 46
	v_lshl_add_u32 v154, v4, 11, s40
	v_readlane_b32 s11, v235, 47
	s_mov_b64 s[6:7], -1
	ds_read_b32 v110, v154 offset:2044
	v_lshl_add_u64 v[114:115], s[10:11], 0, v[2:3]
	v_mul_u32_u24_e32 v1, 3, v4
	v_readlane_b32 s10, v235, 21
	v_ashrrev_i32_e32 v5, 4, v10
	v_lshlrev_b32_e32 v2, 2, v1
	v_mov_b32_e32 v3, v0
	v_readlane_b32 s11, v235, 22
	v_lshlrev_b32_e32 v155, 3, v5
	v_sub_u32_e32 v155, v155, v232
	v_lshlrev_b32_e32 v124, 2, v5
	v_lshl_add_u32 v2, v232, 7, v2
	v_lshl_add_u64 v[122:123], s[10:11], 0, v[2:3]
	v_lshlrev_b32_e32 v2, 7, v4
	v_lshlrev_b32_e32 v4, 8, v4
	v_mov_b32_e32 v5, v0
	v_ashrrev_i32_e32 v125, 31, v124
	v_lshl_add_u32 v4, v232, 11, v4
	v_lshl_add_u64 v[4:5], s[72:73], 0, v[4:5]
	v_lshl_add_u64 v[126:127], v[124:125], 1, v[4:5]
	s_movk_i32 s1, 0x2000
	s_mov_b32 s8, 0
	v_cmp_ne_u32_e64 s[4:5], 0, v10
	v_or_b32_e32 v121, 1, v104
	v_or_b32_e32 v152, 2, v104
	v_or_b32_e32 v153, 3, v104
	v_not_b32_e32 v156, v155
	v_add_u32_e32 v105, 3, v155
	v_add_u32_e32 v116, 2, v155
	v_add_u32_e32 v117, 5, v155
	v_add_u32_e32 v118, 4, v155
	v_add_u32_e32 v119, 7, v155
	v_add_u32_e32 v120, 6, v155
	s_waitcnt lgkmcnt(0)
	v_mov_b32_e32 v111, v110
	s_movk_i32 s33, 0x1000
	s_mov_b32 s2, 0x3d800000
	s_mov_b32 s40, 0xf149f2ca
	s_mov_b32 s42, 0xefa18f08
	s_mov_b32 s43, 0x3c800000
	v_lshlrev_b32_e32 v128, 1, v2
	v_add_u32_e32 v128, v128, v233
	s_mov_b64 s[30:31], 0x2400
	v_mov_b32_e32 v157, 0x4e00
	v_mov_b32_e32 v158, 0x461c4000
	v_mov_b32_e32 v159, 0x1ff
	v_mov_b32_e32 v160, 0xf149f2ca
	s_ashr_i32 s11, s0, 31
	s_mov_b32 s10, s0
	s_lshl_b64 s[10:11], s[10:11], 10
	v_lshl_add_u64 v[2:3], v[106:107], 0, s[10:11]
	global_load_dwordx4 v[4:7], v[2:3], off offset:1024 nt
	global_load_dwordx4 v[176:179], v[2:3], off offset:2048 nt
	global_load_dwordx4 v[252:255], v[2:3], off offset:3072 nt
	s_waitcnt vmcnt(0)
	s_branch .LBB0_784

.LBB0_784:
	s_add_i32 s44, s8, 1
	s_cmp_eq_u32 s8, 7
	v_mov_b32_e32 v8, v36
	v_mov_b32_e32 v9, v37
	v_mov_b32_e32 v10, v38
	v_mov_b32_e32 v11, v39
	v_mov_b32_e32 v12, v32
	v_mov_b32_e32 v13, v33
	v_mov_b32_e32 v14, v34
	v_mov_b32_e32 v15, v35
	v_mov_b32_e32 v16, v28
	v_mov_b32_e32 v17, v29
	v_mov_b32_e32 v18, v30
	v_mov_b32_e32 v19, v31
	v_mov_b32_e32 v20, v24
	v_mov_b32_e32 v21, v25
	v_mov_b32_e32 v22, v26
	v_mov_b32_e32 v23, v27
	s_cbranch_scc1 .LBB0_786
	s_lshl_b32 s9, s44, 10
	s_add_i32 s10, s0, s9
	s_ashr_i32 s11, s10, 31
	s_add_u32 s9, s10, s3
	s_addc_u32 s12, s11, 0
	s_mulk_i32 s12, 0x4e00
	v_mad_u64_u32 v[2:3], s[10:11], s9, v157, v[108:109]
	v_add_u32_e32 v3, s12, v3
	global_load_dwordx4 v[8:11], v[2:3], off nt
	global_load_dwordx4 v[12:15], v[2:3], off offset:16 nt
	global_load_dwordx4 v[16:19], v[2:3], off offset:32 nt
	global_load_dwordx4 v[20:23], v[2:3], off offset:48 nt
.LBB0_786:
	s_lshl_b32 s8, s8, 10
	s_add_i32 s45, s0, s8
	s_ashr_i32 s11, s45, 31
	s_mov_b32 s10, s45
	s_lshl_b64 s[10:11], s[10:11], 10
	v_lshl_add_u64 v[2:3], v[106:107], 0, s[10:11]
	global_load_dwordx4 v[40:43], v[2:3], off nt
	s_ashr_i32 s18, s45, 6
	v_cmp_gt_i32_e64 s[10:11], s18, v104
	s_mov_b64 s[16:17], -1
	s_cmp_lt_i32 s18, 16
	v_cmp_ge_i32_e64 s[14:15], s18, v104
	v_cmp_ge_i32_e64 s[12:13], s18, v152
	v_cmp_ge_i32_e64 s[8:9], s18, v153
	s_cbranch_scc1 .Lx798_c1
	s_add_i32 s18, s18, -1
	v_cmp_gt_i32_e32 vcc, s18, v104
	s_and_b64 vcc, s[4:5], vcc
	s_nop 0
	v_cndmask_b32_e32 v1, v158, v4, vcc
	v_cmp_gt_i32_e32 vcc, s18, v121
	v_cndmask_b32_e64 v3, -1.0, v1, s[14:15]
	s_nop 0
	v_cndmask_b32_e32 v1, v158, v5, vcc
	v_cmp_gt_i32_e32 vcc, s18, v152
	v_cndmask_b32_e64 v4, -1.0, v1, s[10:11]
	v_mov_b32_e32 v5, 0
	v_cndmask_b32_e32 v1, v158, v6, vcc
	v_cmp_gt_i32_e32 vcc, s18, v153
	v_cndmask_b32_e64 v1, -1.0, v1, s[12:13]
	v_mov_b32_e32 v6, 30
	v_cndmask_b32_e32 v2, v158, v7, vcc
	v_cndmask_b32_e64 v2, -1.0, v2, s[8:9]

.Lx800_c0:
	v_cndmask_b32_e64 v1, 0, 1, s[36:37]
	v_cndmask_b32_e64 v2, 0, 1, s[34:35]
	v_cndmask_b32_e64 v3, 0, 1, s[24:25]
	v_cndmask_b32_e64 v40, 0, 1, s[22:23]
	v_cmp_ne_u32_e64 s[12:13], 0, v1
	v_cmp_ne_u32_e64 s[14:15], 0, v2
	v_cmp_ne_u32_e64 s[8:9], 0, v3
	v_cmp_ne_u32_e64 s[10:11], 0, v40
	s_nop 1
	s_or_b64 s[62:63], s[62:63], s[12:13]
	s_or_b64 s[64:65], s[64:65], s[14:15]
	s_or_b64 s[66:67], s[66:67], s[8:9]
	s_or_b64 s[68:69], s[68:69], s[10:11]
	v_writelane_b32 v181, s12, 0
	v_writelane_b32 v181, s13, 1
	v_writelane_b32 v181, s14, 2
	v_writelane_b32 v181, s15, 3
	v_writelane_b32 v181, s8, 4
	v_writelane_b32 v181, s9, 5
	v_writelane_b32 v181, s10, 6
	v_writelane_b32 v181, s11, 7
	s_cmp_eq_u32 s44, 8
	s_cbranch_scc1 .Lx_noimp
	s_lshl_b32 s9, s44, 10
	s_add_i32 s10, s0, s9
	s_ashr_i32 s11, s10, 31
	s_lshl_b64 s[10:11], s[10:11], 10
	v_lshl_add_u64 v[2:3], v[106:107], 0, s[10:11]
	global_load_dwordx4 v[4:7], v[2:3], off offset:1024 nt
	global_load_dwordx4 v[176:179], v[2:3], off offset:2048 nt
	global_load_dwordx4 v[252:255], v[2:3], off offset:3072 nt

.LBB0_813:
	v_mov_b32_e32 v1, v129
	s_nop 1
	v_permlane32_swap_b32_e32 v129, v1
	v_add_f32_e32 v1, v129, v1
	v_mov_b32_e32 v58, v1
	s_nop 1
	v_permlane16_swap_b32_e32 v1, v58
	s_and_saveexec_b64 s[8:9], s[6:7]
	s_cbranch_execz .LBB0_783
	s_ashr_i32 s11, s45, 31
	s_add_u32 s10, s45, s3
	s_addc_u32 s11, s11, 0
	s_lshl_b64 s[12:13], s[10:11], 7
	v_lshl_add_u64 v[2:3], v[122:123], 0, s[12:13]
	global_load_dword v70, v[2:3], off offset:4
	s_mul_i32 s12, s11, 0x4e00
	s_mul_hi_u32 s13, s10, 0x4e00
	s_add_i32 s13, s13, s12
	s_mul_i32 s12, s10, 0x4e00
	s_add_u32 s12, s94, s12
	s_addc_u32 s13, s95, s13
	v_mov_b32_e32 v129, v0
	v_lshl_add_u64 v[2:3], s[12:13], 0, v[128:129]
	v_lshl_add_u64 v[2:3], v[124:125], 1, v[2:3]
	v_add_co_u32_e32 v62, vcc, s1, v2
	s_lshl_b64 s[10:11], s[10:11], 11
	s_nop 0
	v_addc_co_u32_e32 v63, vcc, 0, v3, vcc
	v_lshl_add_u64 v[56:57], v[126:127], 0, s[10:11]
	global_load_dwordx2 v[62:63], v[62:63], off offset:1024 nt
	v_add_f32_e32 v1, v1, v58
	global_load_dwordx2 v[60:61], v[56:57], off nt
	v_div_scale_f32 v71, s[10:11], v1, v1, s43
	v_rcp_f32_e32 v72, v71
	v_div_scale_f32 v73, vcc, s43, v1, s43
	v_fma_f32 v58, -v71, v72, 1.0
	v_fmac_f32_e32 v72, v58, v72
	v_mul_f32_e32 v74, v73, v72
	v_fma_f32 v64, -v71, v74, v73
	v_fmac_f32_e32 v74, v64, v72
	v_fma_f32 v71, -v71, v74, v73
	v_div_fmas_f32 v71, v71, v72, v74
	v_div_fixup_f32 v71, v71, v1, s43
	v_cmp_lt_f32_e32 vcc, 0, v1
	v_lshl_add_u64 v[58:59], v[2:3], 0, s[30:31]
	global_load_dwordx2 v[64:65], v[58:59], off offset:32 nt
	global_load_dwordx2 v[66:67], v[58:59], off offset:64 nt
	global_load_dwordx2 v[68:69], v[58:59], off offset:96 nt
	v_cndmask_b32_e32 v1, 0, v71, vcc
	s_waitcnt vmcnt(5)
	v_mul_f32_e32 v70, 0xbfb8aa3b, v70
	v_exp_f32_e32 v70, v70
	s_waitcnt vmcnt(4)
	v_lshlrev_b32_e32 v73, 16, v62
	v_add_f32_e32 v70, 1.0, v70
	v_rcp_f32_e32 v70, v70
	v_and_b32_e32 v62, 0xffff0000, v62
	s_waitcnt vmcnt(3)
	v_lshlrev_b32_e32 v71, 16, v60
	v_and_b32_e32 v60, 0xffff0000, v60
	v_mul_f32_e32 v1, v1, v70
	v_lshlrev_b32_e32 v74, 16, v63
	v_and_b32_e32 v63, 0xffff0000, v63
	v_fmac_f32_e32 v73, v52, v1
	v_fmac_f32_e32 v62, v53, v1
	v_lshlrev_b32_e32 v72, 16, v61
	v_and_b32_e32 v61, 0xffff0000, v61
	v_fmac_f32_e32 v74, v54, v1
	v_fmac_f32_e32 v63, v55, v1
	v_add_f32_e32 v52, v73, v71
	v_add_f32_e32 v53, v62, v60
	v_add_f32_e32 v54, v74, v72
	v_add_f32_e32 v55, v63, v61
	v_cvt_pk_bf16_f32 v52, v52, v53
	v_cvt_pk_bf16_f32 v53, v54, v55
	global_store_dwordx2 v[2:3], v[52:53], off
	global_load_dwordx2 v[52:53], v[56:57], off offset:32 nt
	s_waitcnt vmcnt(4)
	v_lshlrev_b32_e32 v54, 16, v64
	v_and_b32_e32 v55, 0xffff0000, v64
	v_lshlrev_b32_e32 v60, 16, v65
	v_and_b32_e32 v61, 0xffff0000, v65
	v_fmac_f32_e32 v54, v48, v1
	v_fmac_f32_e32 v55, v49, v1
	v_fmac_f32_e32 v60, v50, v1
	v_fmac_f32_e32 v61, v51, v1
	s_waitcnt vmcnt(0)
	v_lshlrev_b32_e32 v48, 16, v52
	v_and_b32_e32 v49, 0xffff0000, v52
	v_lshlrev_b32_e32 v50, 16, v53
	v_and_b32_e32 v51, 0xffff0000, v53
	v_add_f32_e32 v48, v54, v48
	v_add_f32_e32 v49, v55, v49
	v_add_f32_e32 v50, v60, v50
	v_add_f32_e32 v51, v61, v51
	v_cvt_pk_bf16_f32 v48, v48, v49
	v_cvt_pk_bf16_f32 v49, v50, v51
	global_store_dwordx2 v[2:3], v[48:49], off offset:32
	global_load_dwordx2 v[48:49], v[56:57], off offset:64 nt
	v_lshlrev_b32_e32 v50, 16, v66
	v_and_b32_e32 v51, 0xffff0000, v66
	v_lshlrev_b32_e32 v52, 16, v67
	v_and_b32_e32 v53, 0xffff0000, v67
	v_fmac_f32_e32 v50, v44, v1
	v_fmac_f32_e32 v51, v45, v1
	v_fmac_f32_e32 v52, v46, v1
	v_fmac_f32_e32 v53, v47, v1
	s_waitcnt vmcnt(0)
	v_lshlrev_b32_e32 v44, 16, v48
	v_and_b32_e32 v45, 0xffff0000, v48
	v_lshlrev_b32_e32 v46, 16, v49
	v_and_b32_e32 v47, 0xffff0000, v49
	v_add_f32_e32 v44, v50, v44
	v_add_f32_e32 v45, v51, v45
	v_add_f32_e32 v46, v52, v46
	v_add_f32_e32 v47, v53, v47
	v_cvt_pk_bf16_f32 v44, v44, v45
	v_cvt_pk_bf16_f32 v45, v46, v47
	global_store_dwordx2 v[2:3], v[44:45], off offset:64
	global_load_dwordx2 v[44:45], v[56:57], off offset:96 nt
	s_nop 0
	global_load_dwordx2 v[46:47], v[58:59], off offset:128 nt
	v_lshlrev_b32_e32 v48, 16, v68
	v_and_b32_e32 v49, 0xffff0000, v68
	v_lshlrev_b32_e32 v50, 16, v69
	v_and_b32_e32 v51, 0xffff0000, v69
	v_fmac_f32_e32 v48, v40, v1
	v_fmac_f32_e32 v49, v41, v1
	v_fmac_f32_e32 v50, v42, v1
	v_fmac_f32_e32 v51, v43, v1
	s_waitcnt vmcnt(1)
	v_lshlrev_b32_e32 v40, 16, v44
	v_and_b32_e32 v41, 0xffff0000, v44
	v_lshlrev_b32_e32 v42, 16, v45
	v_and_b32_e32 v43, 0xffff0000, v45
	v_add_f32_e32 v40, v48, v40
	v_add_f32_e32 v41, v49, v41
	v_add_f32_e32 v42, v50, v42
	v_add_f32_e32 v43, v51, v43
	v_cvt_pk_bf16_f32 v40, v40, v41
	v_cvt_pk_bf16_f32 v41, v42, v43
	global_store_dwordx2 v[2:3], v[40:41], off offset:96
	global_load_dwordx2 v[40:41], v[56:57], off offset:128 nt
	s_nop 0
	global_load_dwordx2 v[42:43], v[58:59], off offset:160 nt
	global_load_dwordx2 v[44:45], v[58:59], off offset:192 nt
	global_load_dwordx2 v[48:49], v[58:59], off offset:224 nt
	s_waitcnt vmcnt(5)
	v_lshlrev_b32_e32 v50, 16, v46
	v_and_b32_e32 v46, 0xffff0000, v46
	v_lshlrev_b32_e32 v51, 16, v47
	v_and_b32_e32 v47, 0xffff0000, v47
	v_fmac_f32_e32 v50, v36, v1
	v_fmac_f32_e32 v46, v37, v1
	v_fmac_f32_e32 v51, v38, v1
	v_fmac_f32_e32 v47, v39, v1
	s_waitcnt vmcnt(3)
	v_lshlrev_b32_e32 v36, 16, v40
	v_and_b32_e32 v37, 0xffff0000, v40
	v_lshlrev_b32_e32 v38, 16, v41
	v_and_b32_e32 v39, 0xffff0000, v41
	v_add_f32_e32 v36, v50, v36
	v_add_f32_e32 v37, v46, v37
	v_add_f32_e32 v38, v51, v38
	v_add_f32_e32 v39, v47, v39
	v_cvt_pk_bf16_f32 v36, v36, v37
	v_cvt_pk_bf16_f32 v37, v38, v39
	global_store_dwordx2 v[2:3], v[36:37], off offset:128
	global_load_dwordx2 v[36:37], v[56:57], off offset:160 nt
	s_waitcnt vmcnt(4)
	v_lshlrev_b32_e32 v38, 16, v42
	v_and_b32_e32 v39, 0xffff0000, v42
	v_lshlrev_b32_e32 v40, 16, v43
	v_and_b32_e32 v41, 0xffff0000, v43
	v_fmac_f32_e32 v38, v32, v1
	v_fmac_f32_e32 v39, v33, v1
	v_fmac_f32_e32 v40, v34, v1
	v_fmac_f32_e32 v41, v35, v1
	s_waitcnt vmcnt(0)
	v_lshlrev_b32_e32 v32, 16, v36
	v_and_b32_e32 v33, 0xffff0000, v36
	v_lshlrev_b32_e32 v34, 16, v37
	v_and_b32_e32 v35, 0xffff0000, v37
	v_add_f32_e32 v32, v38, v32
	v_add_f32_e32 v33, v39, v33
	v_add_f32_e32 v34, v40, v34
	v_add_f32_e32 v35, v41, v35
	v_cvt_pk_bf16_f32 v32, v32, v33
	v_cvt_pk_bf16_f32 v33, v34, v35
	global_store_dwordx2 v[2:3], v[32:33], off offset:160
	global_load_dwordx2 v[32:33], v[56:57], off offset:192 nt
	v_lshlrev_b32_e32 v34, 16, v44
	v_and_b32_e32 v35, 0xffff0000, v44
	v_lshlrev_b32_e32 v36, 16, v45
	v_and_b32_e32 v37, 0xffff0000, v45
	v_fmac_f32_e32 v34, v28, v1
	v_fmac_f32_e32 v35, v29, v1
	v_fmac_f32_e32 v36, v30, v1
	v_fmac_f32_e32 v37, v31, v1
	s_waitcnt vmcnt(0)
	v_lshlrev_b32_e32 v28, 16, v32
	v_and_b32_e32 v29, 0xffff0000, v32
	v_lshlrev_b32_e32 v30, 16, v33
	v_and_b32_e32 v31, 0xffff0000, v33
	v_add_f32_e32 v28, v34, v28
	v_add_f32_e32 v29, v35, v29
	v_add_f32_e32 v30, v36, v30
	v_add_f32_e32 v31, v37, v31
	v_cvt_pk_bf16_f32 v28, v28, v29
	v_cvt_pk_bf16_f32 v29, v30, v31
	global_store_dwordx2 v[2:3], v[28:29], off offset:192
	global_load_dwordx2 v[28:29], v[56:57], off offset:224 nt
	v_lshlrev_b32_e32 v30, 16, v48
	v_and_b32_e32 v31, 0xffff0000, v48
	v_lshlrev_b32_e32 v32, 16, v49
	v_and_b32_e32 v33, 0xffff0000, v49
	v_fmac_f32_e32 v30, v24, v1
	v_fmac_f32_e32 v31, v25, v1
	v_fmac_f32_e32 v32, v26, v1
	v_fmac_f32_e32 v33, v27, v1
	s_waitcnt vmcnt(0)
	v_and_b32_e32 v24, 0xffff0000, v28
	v_lshlrev_b32_e32 v25, 16, v29
	v_lshlrev_b32_e32 v1, 16, v28
	v_and_b32_e32 v26, 0xffff0000, v29
	v_add_f32_e32 v24, v31, v24
	v_add_f32_e32 v25, v32, v25
	v_add_f32_e32 v1, v30, v1
	v_add_f32_e32 v26, v33, v26
	v_cvt_pk_bf16_f32 v24, v1, v24
	v_cvt_pk_bf16_f32 v25, v25, v26
	global_store_dwordx2 v[2:3], v[24:25], off offset:224
	s_branch .LBB0_783
